# first modulate pass (x -> bf16 H for layer 0): four rows per step with the next four rows and their scale/shift in flight, instead of one 1 KB chunk load-compute-store at a time
# speedup vs baseline: 1.0085x; 1.0004x over previous
.LBB0_419:
	s_or_b64 exec, exec, s[6:7]
	v_mov_b32_e32 v2, v1
	s_barrier
	v_readlane_b32 s6, v243, 2
	v_readfirstlane_b32 s2, v2
	s_ashr_i32 s2, s2, 6
	s_add_i32 s6, s2, s6
	s_mov_b64 s[10:11], s[0:1]
	s_mov_b64 s[12:13], s[0:1]
	s_mov_b64 s[14:15], s[0:1]
	s_cmpk_gt_i32 s6, 0x7fff
	s_cbranch_scc1 .LBB0_422
	s_load_dwordx2 s[16:17], s[10:11], 0x0
	s_load_dwordx2 s[8:9], s[12:13], 0xd8
	s_load_dwordx2 s[18:19], s[14:15], 0xd8
	s_ashr_i32 s7, s6, 31
	s_lshl_b64 s[10:11], s[6:7], 11
	v_and_b32_e32 v7, 63, v2
	v_lshlrev_b32_e32 v3, 2, v2
	s_waitcnt lgkmcnt(0)
	s_add_u32 s10, s18, s10
	v_mov_b32_e32 v5, 0
	v_lshlrev_b32_e32 v4, 3, v7
	s_addc_u32 s11, s19, s11
	v_and_b32_e32 v6, 0xfc, v3
	v_lshl_add_u64 v[2:3], s[10:11], 0, v[4:5]
	s_mov_b64 s[10:11], 0x5800000
	s_ashr_i32 s77, s76, 31
	v_lshl_add_u64 v[2:3], v[2:3], 0, s[10:11]
	s_lshl_b64 s[10:11], s[76:77], 11
	s_lshl_b64 s[12:13], s[6:7], 12
	s_add_u32 s12, s16, s12
	v_lshlrev_b32_e32 v4, 4, v7
	s_addc_u32 s13, s17, s13
	v_or_b32_e32 v8, 0x100, v6
	v_or_b32_e32 v10, 0x200, v6
	v_or_b32_e32 v12, 0x300, v6
	v_lshl_add_u64 v[4:5], s[12:13], 0, v[4:5]
	s_mov_b64 s[12:13], 0xc00
	v_lshl_add_u64 v[4:5], v[4:5], 0, s[12:13]
	s_lshl_b64 s[12:13], s[76:77], 12
	v_lshlrev_b32_e32 v6, 2, v6
	v_lshlrev_b32_e32 v7, 2, v8
	v_lshlrev_b32_e32 v8, 2, v10
	v_lshlrev_b32_e32 v9, 2, v12
	v_mov_b64_e32 v[214:215], v[4:5]
	v_mov_b64_e32 v[222:223], v[2:3]
	v_lshl_add_u64 v[216:217], v[214:215], 0, s[12:13]
	v_lshl_add_u64 v[224:225], v[222:223], 0, s[10:11]
	v_lshl_add_u64 v[218:219], v[216:217], 0, s[12:13]
	v_lshl_add_u64 v[226:227], v[224:225], 0, s[10:11]
	v_lshl_add_u64 v[220:221], v[218:219], 0, s[12:13]
	v_lshl_add_u64 v[228:229], v[226:227], 0, s[10:11]
	v_lshl_add_u64 v[4:5], v[220:221], 0, s[12:13]
	v_lshl_add_u64 v[2:3], v[228:229], 0, s[10:11]
	s_cmpk_gt_i32 s6, 0x3fff
	s_cselect_b32 s2, 0x9000, 0
	s_add_u32 s14, s8, s2
	s_addc_u32 s15, s9, 0
	s_add_u32 s16, s14, 0x1000
	s_addc_u32 s17, s15, 0
	global_load_dwordx4 v[22:25], v[214:215], off offset:-3072 nt
	global_load_dwordx4 v[26:29], v[214:215], off offset:-2048 nt
	global_load_dwordx4 v[30:33], v[214:215], off offset:-1024 nt
	global_load_dwordx4 v[34:37], v[214:215], off offset:0 nt
	global_load_dwordx4 v[38:41], v[216:217], off offset:-3072 nt
	global_load_dwordx4 v[42:45], v[216:217], off offset:-2048 nt
	global_load_dwordx4 v[46:49], v[216:217], off offset:-1024 nt
	global_load_dwordx4 v[50:53], v[216:217], off offset:0 nt
	global_load_dwordx4 v[54:57], v[218:219], off offset:-3072 nt
	global_load_dwordx4 v[58:61], v[218:219], off offset:-2048 nt
	global_load_dwordx4 v[62:65], v[218:219], off offset:-1024 nt
	global_load_dwordx4 v[66:69], v[218:219], off offset:0 nt
	global_load_dwordx4 v[70:73], v[220:221], off offset:-3072 nt
	global_load_dwordx4 v[74:77], v[220:221], off offset:-2048 nt
	global_load_dwordx4 v[78:81], v[220:221], off offset:-1024 nt
	global_load_dwordx4 v[82:85], v[220:221], off offset:0 nt
	global_load_dwordx4 v[150:153], v6, s[16:17]
	global_load_dwordx4 v[154:157], v7, s[16:17]
	global_load_dwordx4 v[158:161], v8, s[16:17]
	global_load_dwordx4 v[162:165], v9, s[16:17]
	global_load_dwordx4 v[166:169], v6, s[14:15]
	global_load_dwordx4 v[170:173], v6, s[14:15] offset:1024
	global_load_dwordx4 v[174:177], v6, s[14:15] offset:2048
	global_load_dwordx4 v[178:181], v6, s[14:15] offset:3072
	s_lshl_b32 s2, s76, 2
	s_add_i32 s6, s6, s2
	v_mov_b64_e32 v[230:231], v[4:5]
	v_mov_b64_e32 v[244:245], v[2:3]
	v_lshl_add_u64 v[232:233], v[230:231], 0, s[12:13]
	v_lshl_add_u64 v[246:247], v[244:245], 0, s[10:11]
	v_lshl_add_u64 v[234:235], v[232:233], 0, s[12:13]
	v_lshl_add_u64 v[248:249], v[246:247], 0, s[10:11]
	v_lshl_add_u64 v[236:237], v[234:235], 0, s[12:13]
	v_lshl_add_u64 v[250:251], v[248:249], 0, s[10:11]
	v_lshl_add_u64 v[4:5], v[236:237], 0, s[12:13]
	v_lshl_add_u64 v[2:3], v[250:251], 0, s[10:11]
	s_cmpk_gt_i32 s6, 0x3fff
	s_cselect_b32 s2, 0x9000, 0
	s_add_u32 s14, s8, s2
	s_addc_u32 s15, s9, 0
	s_add_u32 s16, s14, 0x1000
	s_addc_u32 s17, s15, 0
	global_load_dwordx4 v[86:89], v[230:231], off offset:-3072 nt
	global_load_dwordx4 v[90:93], v[230:231], off offset:-2048 nt
	global_load_dwordx4 v[94:97], v[230:231], off offset:-1024 nt
	global_load_dwordx4 v[98:101], v[230:231], off offset:0 nt
	global_load_dwordx4 v[102:105], v[232:233], off offset:-3072 nt
	global_load_dwordx4 v[106:109], v[232:233], off offset:-2048 nt
	global_load_dwordx4 v[110:113], v[232:233], off offset:-1024 nt
	global_load_dwordx4 v[114:117], v[232:233], off offset:0 nt
	global_load_dwordx4 v[118:121], v[234:235], off offset:-3072 nt
	global_load_dwordx4 v[122:125], v[234:235], off offset:-2048 nt
	global_load_dwordx4 v[126:129], v[234:235], off offset:-1024 nt
	global_load_dwordx4 v[130:133], v[234:235], off offset:0 nt
	global_load_dwordx4 v[134:137], v[236:237], off offset:-3072 nt
	global_load_dwordx4 v[138:141], v[236:237], off offset:-2048 nt
	global_load_dwordx4 v[142:145], v[236:237], off offset:-1024 nt
	global_load_dwordx4 v[146:149], v[236:237], off offset:0 nt
	global_load_dwordx4 v[182:185], v6, s[16:17]
	global_load_dwordx4 v[186:189], v7, s[16:17]
	global_load_dwordx4 v[190:193], v8, s[16:17]
	global_load_dwordx4 v[194:197], v9, s[16:17]
	global_load_dwordx4 v[198:201], v6, s[14:15]
	global_load_dwordx4 v[202:205], v6, s[14:15] offset:1024
	global_load_dwordx4 v[206:209], v6, s[14:15] offset:2048
	global_load_dwordx4 v[210:213], v6, s[14:15] offset:3072
	s_lshl_b32 s2, s76, 2
	s_add_i32 s6, s6, s2
	s_waitcnt vmcnt(24)
	v_pk_add_f32 v[150:151], v[150:151], 1.0 op_sel_hi:[1,0]
	v_pk_add_f32 v[152:153], v[152:153], 1.0 op_sel_hi:[1,0]
	v_pk_add_f32 v[154:155], v[154:155], 1.0 op_sel_hi:[1,0]
	v_pk_add_f32 v[156:157], v[156:157], 1.0 op_sel_hi:[1,0]
	v_pk_add_f32 v[158:159], v[158:159], 1.0 op_sel_hi:[1,0]
	v_pk_add_f32 v[160:161], v[160:161], 1.0 op_sel_hi:[1,0]
	v_pk_add_f32 v[162:163], v[162:163], 1.0 op_sel_hi:[1,0]
	v_pk_add_f32 v[164:165], v[164:165], 1.0 op_sel_hi:[1,0]
	v_pk_fma_f32 v[22:23], v[22:23], v[150:151], v[166:167]
	v_pk_fma_f32 v[24:25], v[24:25], v[152:153], v[168:169]
	v_pk_fma_f32 v[26:27], v[26:27], v[154:155], v[170:171]
	v_pk_fma_f32 v[28:29], v[28:29], v[156:157], v[172:173]
	v_pk_fma_f32 v[30:31], v[30:31], v[158:159], v[174:175]
	v_pk_fma_f32 v[32:33], v[32:33], v[160:161], v[176:177]
	v_pk_fma_f32 v[34:35], v[34:35], v[162:163], v[178:179]
	v_pk_fma_f32 v[36:37], v[36:37], v[164:165], v[180:181]
	v_cvt_pk_bf16_f32 v22, v22, v23
	v_cvt_pk_bf16_f32 v23, v24, v25
	v_cvt_pk_bf16_f32 v26, v26, v27
	v_cvt_pk_bf16_f32 v27, v28, v29
	v_cvt_pk_bf16_f32 v30, v30, v31
	v_cvt_pk_bf16_f32 v31, v32, v33
	v_cvt_pk_bf16_f32 v34, v34, v35
	v_cvt_pk_bf16_f32 v35, v36, v37
	global_store_dwordx2 v[222:223], v[22:23], off
	global_store_dwordx2 v[222:223], v[26:27], off offset:512
	global_store_dwordx2 v[222:223], v[30:31], off offset:1024
	global_store_dwordx2 v[222:223], v[34:35], off offset:1536
	v_pk_fma_f32 v[38:39], v[38:39], v[150:151], v[166:167]
	v_pk_fma_f32 v[40:41], v[40:41], v[152:153], v[168:169]
	v_pk_fma_f32 v[42:43], v[42:43], v[154:155], v[170:171]
	v_pk_fma_f32 v[44:45], v[44:45], v[156:157], v[172:173]
	v_pk_fma_f32 v[46:47], v[46:47], v[158:159], v[174:175]
	v_pk_fma_f32 v[48:49], v[48:49], v[160:161], v[176:177]
	v_pk_fma_f32 v[50:51], v[50:51], v[162:163], v[178:179]
	v_pk_fma_f32 v[52:53], v[52:53], v[164:165], v[180:181]
	v_cvt_pk_bf16_f32 v38, v38, v39
	v_cvt_pk_bf16_f32 v39, v40, v41
	v_cvt_pk_bf16_f32 v42, v42, v43
	v_cvt_pk_bf16_f32 v43, v44, v45
	v_cvt_pk_bf16_f32 v46, v46, v47
	v_cvt_pk_bf16_f32 v47, v48, v49
	v_cvt_pk_bf16_f32 v50, v50, v51
	v_cvt_pk_bf16_f32 v51, v52, v53
	global_store_dwordx2 v[224:225], v[38:39], off
	global_store_dwordx2 v[224:225], v[42:43], off offset:512
	global_store_dwordx2 v[224:225], v[46:47], off offset:1024
	global_store_dwordx2 v[224:225], v[50:51], off offset:1536
	v_pk_fma_f32 v[54:55], v[54:55], v[150:151], v[166:167]
	v_pk_fma_f32 v[56:57], v[56:57], v[152:153], v[168:169]
	v_pk_fma_f32 v[58:59], v[58:59], v[154:155], v[170:171]
	v_pk_fma_f32 v[60:61], v[60:61], v[156:157], v[172:173]
	v_pk_fma_f32 v[62:63], v[62:63], v[158:159], v[174:175]
	v_pk_fma_f32 v[64:65], v[64:65], v[160:161], v[176:177]
	v_pk_fma_f32 v[66:67], v[66:67], v[162:163], v[178:179]
	v_pk_fma_f32 v[68:69], v[68:69], v[164:165], v[180:181]
	v_cvt_pk_bf16_f32 v54, v54, v55
	v_cvt_pk_bf16_f32 v55, v56, v57
	v_cvt_pk_bf16_f32 v58, v58, v59
	v_cvt_pk_bf16_f32 v59, v60, v61
	v_cvt_pk_bf16_f32 v62, v62, v63
	v_cvt_pk_bf16_f32 v63, v64, v65
	v_cvt_pk_bf16_f32 v66, v66, v67
	v_cvt_pk_bf16_f32 v67, v68, v69
	global_store_dwordx2 v[226:227], v[54:55], off
	global_store_dwordx2 v[226:227], v[58:59], off offset:512
	global_store_dwordx2 v[226:227], v[62:63], off offset:1024
	global_store_dwordx2 v[226:227], v[66:67], off offset:1536
	v_pk_fma_f32 v[70:71], v[70:71], v[150:151], v[166:167]
	v_pk_fma_f32 v[72:73], v[72:73], v[152:153], v[168:169]
	v_pk_fma_f32 v[74:75], v[74:75], v[154:155], v[170:171]
	v_pk_fma_f32 v[76:77], v[76:77], v[156:157], v[172:173]
	v_pk_fma_f32 v[78:79], v[78:79], v[158:159], v[174:175]
	v_pk_fma_f32 v[80:81], v[80:81], v[160:161], v[176:177]
	v_pk_fma_f32 v[82:83], v[82:83], v[162:163], v[178:179]
	v_pk_fma_f32 v[84:85], v[84:85], v[164:165], v[180:181]
	v_cvt_pk_bf16_f32 v70, v70, v71
	v_cvt_pk_bf16_f32 v71, v72, v73
	v_cvt_pk_bf16_f32 v74, v74, v75
	v_cvt_pk_bf16_f32 v75, v76, v77
	v_cvt_pk_bf16_f32 v78, v78, v79
	v_cvt_pk_bf16_f32 v79, v80, v81
	v_cvt_pk_bf16_f32 v82, v82, v83
	v_cvt_pk_bf16_f32 v83, v84, v85
	global_store_dwordx2 v[228:229], v[70:71], off
	global_store_dwordx2 v[228:229], v[74:75], off offset:512
	global_store_dwordx2 v[228:229], v[78:79], off offset:1024
	global_store_dwordx2 v[228:229], v[82:83], off offset:1536
	s_waitcnt vmcnt(16)
	v_mov_b64_e32 v[214:215], v[4:5]
	v_mov_b64_e32 v[222:223], v[2:3]
	v_lshl_add_u64 v[216:217], v[214:215], 0, s[12:13]
	v_lshl_add_u64 v[224:225], v[222:223], 0, s[10:11]
	v_lshl_add_u64 v[218:219], v[216:217], 0, s[12:13]
	v_lshl_add_u64 v[226:227], v[224:225], 0, s[10:11]
	v_lshl_add_u64 v[220:221], v[218:219], 0, s[12:13]
	v_lshl_add_u64 v[228:229], v[226:227], 0, s[10:11]
	v_lshl_add_u64 v[4:5], v[220:221], 0, s[12:13]
	v_lshl_add_u64 v[2:3], v[228:229], 0, s[10:11]
	s_cmpk_gt_i32 s6, 0x3fff
	s_cselect_b32 s2, 0x9000, 0
	s_add_u32 s14, s8, s2
	s_addc_u32 s15, s9, 0
	s_add_u32 s16, s14, 0x1000
	s_addc_u32 s17, s15, 0
	global_load_dwordx4 v[22:25], v[214:215], off offset:-3072 nt
	global_load_dwordx4 v[26:29], v[214:215], off offset:-2048 nt
	global_load_dwordx4 v[30:33], v[214:215], off offset:-1024 nt
	global_load_dwordx4 v[34:37], v[214:215], off offset:0 nt
	global_load_dwordx4 v[38:41], v[216:217], off offset:-3072 nt
	global_load_dwordx4 v[42:45], v[216:217], off offset:-2048 nt
	global_load_dwordx4 v[46:49], v[216:217], off offset:-1024 nt
	global_load_dwordx4 v[50:53], v[216:217], off offset:0 nt
	global_load_dwordx4 v[54:57], v[218:219], off offset:-3072 nt
	global_load_dwordx4 v[58:61], v[218:219], off offset:-2048 nt
	global_load_dwordx4 v[62:65], v[218:219], off offset:-1024 nt
	global_load_dwordx4 v[66:69], v[218:219], off offset:0 nt
	global_load_dwordx4 v[70:73], v[220:221], off offset:-3072 nt
	global_load_dwordx4 v[74:77], v[220:221], off offset:-2048 nt
	global_load_dwordx4 v[78:81], v[220:221], off offset:-1024 nt
	global_load_dwordx4 v[82:85], v[220:221], off offset:0 nt
	global_load_dwordx4 v[150:153], v6, s[16:17]
	global_load_dwordx4 v[154:157], v7, s[16:17]
	global_load_dwordx4 v[158:161], v8, s[16:17]
	global_load_dwordx4 v[162:165], v9, s[16:17]
	global_load_dwordx4 v[166:169], v6, s[14:15]
	global_load_dwordx4 v[170:173], v6, s[14:15] offset:1024
	global_load_dwordx4 v[174:177], v6, s[14:15] offset:2048
	global_load_dwordx4 v[178:181], v6, s[14:15] offset:3072
	s_lshl_b32 s2, s76, 2
	s_add_i32 s6, s6, s2
	v_pk_add_f32 v[182:183], v[182:183], 1.0 op_sel_hi:[1,0]
	v_pk_add_f32 v[184:185], v[184:185], 1.0 op_sel_hi:[1,0]
	v_pk_add_f32 v[186:187], v[186:187], 1.0 op_sel_hi:[1,0]
	v_pk_add_f32 v[188:189], v[188:189], 1.0 op_sel_hi:[1,0]
	v_pk_add_f32 v[190:191], v[190:191], 1.0 op_sel_hi:[1,0]
	v_pk_add_f32 v[192:193], v[192:193], 1.0 op_sel_hi:[1,0]
	v_pk_add_f32 v[194:195], v[194:195], 1.0 op_sel_hi:[1,0]
	v_pk_add_f32 v[196:197], v[196:197], 1.0 op_sel_hi:[1,0]
	v_pk_fma_f32 v[86:87], v[86:87], v[182:183], v[198:199]
	v_pk_fma_f32 v[88:89], v[88:89], v[184:185], v[200:201]
	v_pk_fma_f32 v[90:91], v[90:91], v[186:187], v[202:203]
	v_pk_fma_f32 v[92:93], v[92:93], v[188:189], v[204:205]
	v_pk_fma_f32 v[94:95], v[94:95], v[190:191], v[206:207]
	v_pk_fma_f32 v[96:97], v[96:97], v[192:193], v[208:209]
	v_pk_fma_f32 v[98:99], v[98:99], v[194:195], v[210:211]
	v_pk_fma_f32 v[100:101], v[100:101], v[196:197], v[212:213]
	v_cvt_pk_bf16_f32 v86, v86, v87
	v_cvt_pk_bf16_f32 v87, v88, v89
	v_cvt_pk_bf16_f32 v90, v90, v91
	v_cvt_pk_bf16_f32 v91, v92, v93
	v_cvt_pk_bf16_f32 v94, v94, v95
	v_cvt_pk_bf16_f32 v95, v96, v97
	v_cvt_pk_bf16_f32 v98, v98, v99
	v_cvt_pk_bf16_f32 v99, v100, v101
	global_store_dwordx2 v[244:245], v[86:87], off
	global_store_dwordx2 v[244:245], v[90:91], off offset:512
	global_store_dwordx2 v[244:245], v[94:95], off offset:1024
	global_store_dwordx2 v[244:245], v[98:99], off offset:1536
	v_pk_fma_f32 v[102:103], v[102:103], v[182:183], v[198:199]
	v_pk_fma_f32 v[104:105], v[104:105], v[184:185], v[200:201]
	v_pk_fma_f32 v[106:107], v[106:107], v[186:187], v[202:203]
	v_pk_fma_f32 v[108:109], v[108:109], v[188:189], v[204:205]
	v_pk_fma_f32 v[110:111], v[110:111], v[190:191], v[206:207]
	v_pk_fma_f32 v[112:113], v[112:113], v[192:193], v[208:209]
	v_pk_fma_f32 v[114:115], v[114:115], v[194:195], v[210:211]
	v_pk_fma_f32 v[116:117], v[116:117], v[196:197], v[212:213]
	v_cvt_pk_bf16_f32 v102, v102, v103
	v_cvt_pk_bf16_f32 v103, v104, v105
	v_cvt_pk_bf16_f32 v106, v106, v107
	v_cvt_pk_bf16_f32 v107, v108, v109
	v_cvt_pk_bf16_f32 v110, v110, v111
	v_cvt_pk_bf16_f32 v111, v112, v113
	v_cvt_pk_bf16_f32 v114, v114, v115
	v_cvt_pk_bf16_f32 v115, v116, v117
	global_store_dwordx2 v[246:247], v[102:103], off
	global_store_dwordx2 v[246:247], v[106:107], off offset:512
	global_store_dwordx2 v[246:247], v[110:111], off offset:1024
	global_store_dwordx2 v[246:247], v[114:115], off offset:1536
	v_pk_fma_f32 v[118:119], v[118:119], v[182:183], v[198:199]
	v_pk_fma_f32 v[120:121], v[120:121], v[184:185], v[200:201]
	v_pk_fma_f32 v[122:123], v[122:123], v[186:187], v[202:203]
	v_pk_fma_f32 v[124:125], v[124:125], v[188:189], v[204:205]
	v_pk_fma_f32 v[126:127], v[126:127], v[190:191], v[206:207]
	v_pk_fma_f32 v[128:129], v[128:129], v[192:193], v[208:209]
	v_pk_fma_f32 v[130:131], v[130:131], v[194:195], v[210:211]
	v_pk_fma_f32 v[132:133], v[132:133], v[196:197], v[212:213]
	v_cvt_pk_bf16_f32 v118, v118, v119
	v_cvt_pk_bf16_f32 v119, v120, v121
	v_cvt_pk_bf16_f32 v122, v122, v123
	v_cvt_pk_bf16_f32 v123, v124, v125
	v_cvt_pk_bf16_f32 v126, v126, v127
	v_cvt_pk_bf16_f32 v127, v128, v129
	v_cvt_pk_bf16_f32 v130, v130, v131
	v_cvt_pk_bf16_f32 v131, v132, v133
	global_store_dwordx2 v[248:249], v[118:119], off
	global_store_dwordx2 v[248:249], v[122:123], off offset:512
	global_store_dwordx2 v[248:249], v[126:127], off offset:1024
	global_store_dwordx2 v[248:249], v[130:131], off offset:1536
	v_pk_fma_f32 v[134:135], v[134:135], v[182:183], v[198:199]
	v_pk_fma_f32 v[136:137], v[136:137], v[184:185], v[200:201]
	v_pk_fma_f32 v[138:139], v[138:139], v[186:187], v[202:203]
	v_pk_fma_f32 v[140:141], v[140:141], v[188:189], v[204:205]
	v_pk_fma_f32 v[142:143], v[142:143], v[190:191], v[206:207]
	v_pk_fma_f32 v[144:145], v[144:145], v[192:193], v[208:209]
	v_pk_fma_f32 v[146:147], v[146:147], v[194:195], v[210:211]
	v_pk_fma_f32 v[148:149], v[148:149], v[196:197], v[212:213]
	v_cvt_pk_bf16_f32 v134, v134, v135
	v_cvt_pk_bf16_f32 v135, v136, v137
	v_cvt_pk_bf16_f32 v138, v138, v139
	v_cvt_pk_bf16_f32 v139, v140, v141
	v_cvt_pk_bf16_f32 v142, v142, v143
	v_cvt_pk_bf16_f32 v143, v144, v145
	v_cvt_pk_bf16_f32 v146, v146, v147
	v_cvt_pk_bf16_f32 v147, v148, v149
	global_store_dwordx2 v[250:251], v[134:135], off
	global_store_dwordx2 v[250:251], v[138:139], off offset:512
	global_store_dwordx2 v[250:251], v[142:143], off offset:1024
	global_store_dwordx2 v[250:251], v[146:147], off offset:1536
	s_waitcnt vmcnt(16)
	v_mov_b64_e32 v[230:231], v[4:5]
	v_mov_b64_e32 v[244:245], v[2:3]
	v_lshl_add_u64 v[232:233], v[230:231], 0, s[12:13]
	v_lshl_add_u64 v[246:247], v[244:245], 0, s[10:11]
	v_lshl_add_u64 v[234:235], v[232:233], 0, s[12:13]
	v_lshl_add_u64 v[248:249], v[246:247], 0, s[10:11]
	v_lshl_add_u64 v[236:237], v[234:235], 0, s[12:13]
	v_lshl_add_u64 v[250:251], v[248:249], 0, s[10:11]
	v_lshl_add_u64 v[4:5], v[236:237], 0, s[12:13]
	v_lshl_add_u64 v[2:3], v[250:251], 0, s[10:11]
	s_cmpk_gt_i32 s6, 0x3fff
	s_cselect_b32 s2, 0x9000, 0
	s_add_u32 s14, s8, s2
	s_addc_u32 s15, s9, 0
	s_add_u32 s16, s14, 0x1000
	s_addc_u32 s17, s15, 0
	global_load_dwordx4 v[86:89], v[230:231], off offset:-3072 nt
	global_load_dwordx4 v[90:93], v[230:231], off offset:-2048 nt
	global_load_dwordx4 v[94:97], v[230:231], off offset:-1024 nt
	global_load_dwordx4 v[98:101], v[230:231], off offset:0 nt
	global_load_dwordx4 v[102:105], v[232:233], off offset:-3072 nt
	global_load_dwordx4 v[106:109], v[232:233], off offset:-2048 nt
	global_load_dwordx4 v[110:113], v[232:233], off offset:-1024 nt
	global_load_dwordx4 v[114:117], v[232:233], off offset:0 nt
	global_load_dwordx4 v[118:121], v[234:235], off offset:-3072 nt
	global_load_dwordx4 v[122:125], v[234:235], off offset:-2048 nt
	global_load_dwordx4 v[126:129], v[234:235], off offset:-1024 nt
	global_load_dwordx4 v[130:133], v[234:235], off offset:0 nt
	global_load_dwordx4 v[134:137], v[236:237], off offset:-3072 nt
	global_load_dwordx4 v[138:141], v[236:237], off offset:-2048 nt
	global_load_dwordx4 v[142:145], v[236:237], off offset:-1024 nt
	global_load_dwordx4 v[146:149], v[236:237], off offset:0 nt
	global_load_dwordx4 v[182:185], v6, s[16:17]
	global_load_dwordx4 v[186:189], v7, s[16:17]
	global_load_dwordx4 v[190:193], v8, s[16:17]
	global_load_dwordx4 v[194:197], v9, s[16:17]
	global_load_dwordx4 v[198:201], v6, s[14:15]
	global_load_dwordx4 v[202:205], v6, s[14:15] offset:1024
	global_load_dwordx4 v[206:209], v6, s[14:15] offset:2048
	global_load_dwordx4 v[210:213], v6, s[14:15] offset:3072
	s_lshl_b32 s2, s76, 2
	s_add_i32 s6, s6, s2
	v_pk_add_f32 v[150:151], v[150:151], 1.0 op_sel_hi:[1,0]
	v_pk_add_f32 v[152:153], v[152:153], 1.0 op_sel_hi:[1,0]
	v_pk_add_f32 v[154:155], v[154:155], 1.0 op_sel_hi:[1,0]
	v_pk_add_f32 v[156:157], v[156:157], 1.0 op_sel_hi:[1,0]
	v_pk_add_f32 v[158:159], v[158:159], 1.0 op_sel_hi:[1,0]
	v_pk_add_f32 v[160:161], v[160:161], 1.0 op_sel_hi:[1,0]
	v_pk_add_f32 v[162:163], v[162:163], 1.0 op_sel_hi:[1,0]
	v_pk_add_f32 v[164:165], v[164:165], 1.0 op_sel_hi:[1,0]
	v_pk_fma_f32 v[22:23], v[22:23], v[150:151], v[166:167]
	v_pk_fma_f32 v[24:25], v[24:25], v[152:153], v[168:169]
	v_pk_fma_f32 v[26:27], v[26:27], v[154:155], v[170:171]
	v_pk_fma_f32 v[28:29], v[28:29], v[156:157], v[172:173]
	v_pk_fma_f32 v[30:31], v[30:31], v[158:159], v[174:175]
	v_pk_fma_f32 v[32:33], v[32:33], v[160:161], v[176:177]
	v_pk_fma_f32 v[34:35], v[34:35], v[162:163], v[178:179]
	v_pk_fma_f32 v[36:37], v[36:37], v[164:165], v[180:181]
	v_cvt_pk_bf16_f32 v22, v22, v23
	v_cvt_pk_bf16_f32 v23, v24, v25
	v_cvt_pk_bf16_f32 v26, v26, v27
	v_cvt_pk_bf16_f32 v27, v28, v29
	v_cvt_pk_bf16_f32 v30, v30, v31
	v_cvt_pk_bf16_f32 v31, v32, v33
	v_cvt_pk_bf16_f32 v34, v34, v35
	v_cvt_pk_bf16_f32 v35, v36, v37
	global_store_dwordx2 v[222:223], v[22:23], off
	global_store_dwordx2 v[222:223], v[26:27], off offset:512
	global_store_dwordx2 v[222:223], v[30:31], off offset:1024
	global_store_dwordx2 v[222:223], v[34:35], off offset:1536
	v_pk_fma_f32 v[38:39], v[38:39], v[150:151], v[166:167]
	v_pk_fma_f32 v[40:41], v[40:41], v[152:153], v[168:169]
	v_pk_fma_f32 v[42:43], v[42:43], v[154:155], v[170:171]
	v_pk_fma_f32 v[44:45], v[44:45], v[156:157], v[172:173]
	v_pk_fma_f32 v[46:47], v[46:47], v[158:159], v[174:175]
	v_pk_fma_f32 v[48:49], v[48:49], v[160:161], v[176:177]
	v_pk_fma_f32 v[50:51], v[50:51], v[162:163], v[178:179]
	v_pk_fma_f32 v[52:53], v[52:53], v[164:165], v[180:181]
	v_cvt_pk_bf16_f32 v38, v38, v39
	v_cvt_pk_bf16_f32 v39, v40, v41
	v_cvt_pk_bf16_f32 v42, v42, v43
	v_cvt_pk_bf16_f32 v43, v44, v45
	v_cvt_pk_bf16_f32 v46, v46, v47
	v_cvt_pk_bf16_f32 v47, v48, v49
	v_cvt_pk_bf16_f32 v50, v50, v51
	v_cvt_pk_bf16_f32 v51, v52, v53
	global_store_dwordx2 v[224:225], v[38:39], off
	global_store_dwordx2 v[224:225], v[42:43], off offset:512
	global_store_dwordx2 v[224:225], v[46:47], off offset:1024
	global_store_dwordx2 v[224:225], v[50:51], off offset:1536
	v_pk_fma_f32 v[54:55], v[54:55], v[150:151], v[166:167]
	v_pk_fma_f32 v[56:57], v[56:57], v[152:153], v[168:169]
	v_pk_fma_f32 v[58:59], v[58:59], v[154:155], v[170:171]
	v_pk_fma_f32 v[60:61], v[60:61], v[156:157], v[172:173]
	v_pk_fma_f32 v[62:63], v[62:63], v[158:159], v[174:175]
	v_pk_fma_f32 v[64:65], v[64:65], v[160:161], v[176:177]
	v_pk_fma_f32 v[66:67], v[66:67], v[162:163], v[178:179]
	v_pk_fma_f32 v[68:69], v[68:69], v[164:165], v[180:181]
	v_cvt_pk_bf16_f32 v54, v54, v55
	v_cvt_pk_bf16_f32 v55, v56, v57
	v_cvt_pk_bf16_f32 v58, v58, v59
	v_cvt_pk_bf16_f32 v59, v60, v61
	v_cvt_pk_bf16_f32 v62, v62, v63
	v_cvt_pk_bf16_f32 v63, v64, v65
	v_cvt_pk_bf16_f32 v66, v66, v67
	v_cvt_pk_bf16_f32 v67, v68, v69
	global_store_dwordx2 v[226:227], v[54:55], off
	global_store_dwordx2 v[226:227], v[58:59], off offset:512
	global_store_dwordx2 v[226:227], v[62:63], off offset:1024
	global_store_dwordx2 v[226:227], v[66:67], off offset:1536
	v_pk_fma_f32 v[70:71], v[70:71], v[150:151], v[166:167]
	v_pk_fma_f32 v[72:73], v[72:73], v[152:153], v[168:169]
	v_pk_fma_f32 v[74:75], v[74:75], v[154:155], v[170:171]
	v_pk_fma_f32 v[76:77], v[76:77], v[156:157], v[172:173]
	v_pk_fma_f32 v[78:79], v[78:79], v[158:159], v[174:175]
	v_pk_fma_f32 v[80:81], v[80:81], v[160:161], v[176:177]
	v_pk_fma_f32 v[82:83], v[82:83], v[162:163], v[178:179]
	v_pk_fma_f32 v[84:85], v[84:85], v[164:165], v[180:181]
	v_cvt_pk_bf16_f32 v70, v70, v71
	v_cvt_pk_bf16_f32 v71, v72, v73
	v_cvt_pk_bf16_f32 v74, v74, v75
	v_cvt_pk_bf16_f32 v75, v76, v77
	v_cvt_pk_bf16_f32 v78, v78, v79
	v_cvt_pk_bf16_f32 v79, v80, v81
	v_cvt_pk_bf16_f32 v82, v82, v83
	v_cvt_pk_bf16_f32 v83, v84, v85
	global_store_dwordx2 v[228:229], v[70:71], off
	global_store_dwordx2 v[228:229], v[74:75], off offset:512
	global_store_dwordx2 v[228:229], v[78:79], off offset:1024
	global_store_dwordx2 v[228:229], v[82:83], off offset:1536
	s_waitcnt vmcnt(16)
	v_pk_add_f32 v[182:183], v[182:183], 1.0 op_sel_hi:[1,0]
	v_pk_add_f32 v[184:185], v[184:185], 1.0 op_sel_hi:[1,0]
	v_pk_add_f32 v[186:187], v[186:187], 1.0 op_sel_hi:[1,0]
	v_pk_add_f32 v[188:189], v[188:189], 1.0 op_sel_hi:[1,0]
	v_pk_add_f32 v[190:191], v[190:191], 1.0 op_sel_hi:[1,0]
	v_pk_add_f32 v[192:193], v[192:193], 1.0 op_sel_hi:[1,0]
	v_pk_add_f32 v[194:195], v[194:195], 1.0 op_sel_hi:[1,0]
	v_pk_add_f32 v[196:197], v[196:197], 1.0 op_sel_hi:[1,0]
	v_pk_fma_f32 v[86:87], v[86:87], v[182:183], v[198:199]
	v_pk_fma_f32 v[88:89], v[88:89], v[184:185], v[200:201]
	v_pk_fma_f32 v[90:91], v[90:91], v[186:187], v[202:203]
	v_pk_fma_f32 v[92:93], v[92:93], v[188:189], v[204:205]
	v_pk_fma_f32 v[94:95], v[94:95], v[190:191], v[206:207]
	v_pk_fma_f32 v[96:97], v[96:97], v[192:193], v[208:209]
	v_pk_fma_f32 v[98:99], v[98:99], v[194:195], v[210:211]
	v_pk_fma_f32 v[100:101], v[100:101], v[196:197], v[212:213]
	v_cvt_pk_bf16_f32 v86, v86, v87
	v_cvt_pk_bf16_f32 v87, v88, v89
	v_cvt_pk_bf16_f32 v90, v90, v91
	v_cvt_pk_bf16_f32 v91, v92, v93
	v_cvt_pk_bf16_f32 v94, v94, v95
	v_cvt_pk_bf16_f32 v95, v96, v97
	v_cvt_pk_bf16_f32 v98, v98, v99
	v_cvt_pk_bf16_f32 v99, v100, v101
	global_store_dwordx2 v[244:245], v[86:87], off
	global_store_dwordx2 v[244:245], v[90:91], off offset:512
	global_store_dwordx2 v[244:245], v[94:95], off offset:1024
	global_store_dwordx2 v[244:245], v[98:99], off offset:1536
	v_pk_fma_f32 v[102:103], v[102:103], v[182:183], v[198:199]
	v_pk_fma_f32 v[104:105], v[104:105], v[184:185], v[200:201]
	v_pk_fma_f32 v[106:107], v[106:107], v[186:187], v[202:203]
	v_pk_fma_f32 v[108:109], v[108:109], v[188:189], v[204:205]
	v_pk_fma_f32 v[110:111], v[110:111], v[190:191], v[206:207]
	v_pk_fma_f32 v[112:113], v[112:113], v[192:193], v[208:209]
	v_pk_fma_f32 v[114:115], v[114:115], v[194:195], v[210:211]
	v_pk_fma_f32 v[116:117], v[116:117], v[196:197], v[212:213]
	v_cvt_pk_bf16_f32 v102, v102, v103
	v_cvt_pk_bf16_f32 v103, v104, v105
	v_cvt_pk_bf16_f32 v106, v106, v107
	v_cvt_pk_bf16_f32 v107, v108, v109
	v_cvt_pk_bf16_f32 v110, v110, v111
	v_cvt_pk_bf16_f32 v111, v112, v113
	v_cvt_pk_bf16_f32 v114, v114, v115
	v_cvt_pk_bf16_f32 v115, v116, v117
	global_store_dwordx2 v[246:247], v[102:103], off
	global_store_dwordx2 v[246:247], v[106:107], off offset:512
	global_store_dwordx2 v[246:247], v[110:111], off offset:1024
	global_store_dwordx2 v[246:247], v[114:115], off offset:1536
	v_pk_fma_f32 v[118:119], v[118:119], v[182:183], v[198:199]
	v_pk_fma_f32 v[120:121], v[120:121], v[184:185], v[200:201]
	v_pk_fma_f32 v[122:123], v[122:123], v[186:187], v[202:203]
	v_pk_fma_f32 v[124:125], v[124:125], v[188:189], v[204:205]
	v_pk_fma_f32 v[126:127], v[126:127], v[190:191], v[206:207]
	v_pk_fma_f32 v[128:129], v[128:129], v[192:193], v[208:209]
	v_pk_fma_f32 v[130:131], v[130:131], v[194:195], v[210:211]
	v_pk_fma_f32 v[132:133], v[132:133], v[196:197], v[212:213]
	v_cvt_pk_bf16_f32 v118, v118, v119
	v_cvt_pk_bf16_f32 v119, v120, v121
	v_cvt_pk_bf16_f32 v122, v122, v123
	v_cvt_pk_bf16_f32 v123, v124, v125
	v_cvt_pk_bf16_f32 v126, v126, v127
	v_cvt_pk_bf16_f32 v127, v128, v129
	v_cvt_pk_bf16_f32 v130, v130, v131
	v_cvt_pk_bf16_f32 v131, v132, v133
	global_store_dwordx2 v[248:249], v[118:119], off
	global_store_dwordx2 v[248:249], v[122:123], off offset:512
	global_store_dwordx2 v[248:249], v[126:127], off offset:1024
	global_store_dwordx2 v[248:249], v[130:131], off offset:1536
	v_pk_fma_f32 v[134:135], v[134:135], v[182:183], v[198:199]
	v_pk_fma_f32 v[136:137], v[136:137], v[184:185], v[200:201]
	v_pk_fma_f32 v[138:139], v[138:139], v[186:187], v[202:203]
	v_pk_fma_f32 v[140:141], v[140:141], v[188:189], v[204:205]
	v_pk_fma_f32 v[142:143], v[142:143], v[190:191], v[206:207]
	v_pk_fma_f32 v[144:145], v[144:145], v[192:193], v[208:209]
	v_pk_fma_f32 v[146:147], v[146:147], v[194:195], v[210:211]
	v_pk_fma_f32 v[148:149], v[148:149], v[196:197], v[212:213]
	v_cvt_pk_bf16_f32 v134, v134, v135
	v_cvt_pk_bf16_f32 v135, v136, v137
	v_cvt_pk_bf16_f32 v138, v138, v139
	v_cvt_pk_bf16_f32 v139, v140, v141
	v_cvt_pk_bf16_f32 v142, v142, v143
	v_cvt_pk_bf16_f32 v143, v144, v145
	v_cvt_pk_bf16_f32 v146, v146, v147
	v_cvt_pk_bf16_f32 v147, v148, v149
	global_store_dwordx2 v[250:251], v[134:135], off
	global_store_dwordx2 v[250:251], v[138:139], off offset:512
	global_store_dwordx2 v[250:251], v[142:143], off offset:1024
	global_store_dwordx2 v[250:251], v[146:147], off offset:1536
